# phase0: conv_w loads issued 8 at a time instead of load-wait-load, RMSNorm gain vectors hoisted out of the row loop (vmcnt re-derived)
# speedup vs baseline: 1.0157x; 1.0157x over previous
; template <int MODE> __device__ __forceinline__ void conv_w(const float* W, int K, int N, bf16_t* Wt, int NP, LAS float* scr, int gw, int ngw, int lane) {
;     ...
;     for (int it = gw; it < nitems; it += ngw) {
;         const int kb = it / nblk, nb = it % nblk, k0 = 64 * kb, np0 = 32 * nb, n0 = wmap<MODE>(np0);
; #pragma unroll 8
;         for (int i = 0; i < 32; ++i) { const int kk = 2 * i + (lane >> 5); scr[kk * 33 + (lane & 31)] = n0 >= 0 ? W[(size_t)(k0 + kk) * N + n0 + (lane & 31)] : 0.f; }
;         asm volatile("s_waitcnt lgkmcnt(0)" ::: "memory");
.LBB0_7:
	s_or_b64 exec, exec, s[6:7]
	s_add_i32 s14, s14, 16
	s_waitcnt vmcnt(0)
	s_nop 0
	s_cmp_eq_u32 s14, 64
	v_add_u32_e32 v11, 0x840, v11
	s_cbranch_scc1 .LBB0_5
.LBB0_8:
	v_mov_b32_e32 v120, 0
	v_mov_b32_e32 v121, 0
	v_mov_b32_e32 v122, 0
	v_mov_b32_e32 v123, 0
	v_mov_b32_e32 v124, 0
	v_mov_b32_e32 v125, 0
	v_mov_b32_e32 v126, 0
	v_mov_b32_e32 v127, 0
	s_and_saveexec_b64 s[6:7], vcc
	s_cbranch_execz .Lmy_cw0_skip
	v_add_u32_e32 v22, s14, v4
	v_mad_i64_i32 v[22:23], s[16:17], v22, s11, v[12:13]
	global_load_dword v120, v[22:23], off
	v_add3_u32 v21, v4, s14, 2
	v_mad_i64_i32 v[22:23], s[16:17], v21, s11, v[12:13]
	global_load_dword v121, v[22:23], off
	v_add3_u32 v22, v4, s14, 4
	v_mad_i64_i32 v[22:23], s[16:17], v22, s11, v[12:13]
	global_load_dword v122, v[22:23], off
	v_add3_u32 v21, v4, s14, 6
	v_mad_i64_i32 v[22:23], s[16:17], v21, s11, v[12:13]
	global_load_dword v123, v[22:23], off
	v_add3_u32 v22, v4, s14, 8
	v_mad_i64_i32 v[22:23], s[16:17], v22, s11, v[12:13]
	global_load_dword v124, v[22:23], off
	v_add3_u32 v21, v4, s14, 10
	v_mad_i64_i32 v[22:23], s[16:17], v21, s11, v[12:13]
	global_load_dword v125, v[22:23], off
	v_add3_u32 v22, v4, s14, 12
	v_mad_i64_i32 v[22:23], s[16:17], v22, s11, v[12:13]
	global_load_dword v126, v[22:23], off
	v_add3_u32 v21, v4, s14, 14
	v_mad_i64_i32 v[22:23], s[16:17], v21, s11, v[12:13]
	global_load_dword v127, v[22:23], off
.Lmy_cw0_skip:
	s_or_b64 exec, exec, s[6:7]
	s_waitcnt vmcnt(0)
	ds_write_b32 v11, v120
	ds_write_b32 v11, v121 offset:264
	ds_write_b32 v11, v122 offset:528
	ds_write_b32 v11, v123 offset:792
	ds_write_b32 v11, v124 offset:1056
	ds_write_b32 v11, v125 offset:1320
	ds_write_b32 v11, v126 offset:1584
	ds_write_b32 v11, v127 offset:1848
	s_branch .LBB0_7

; template <int MODE> __device__ __forceinline__ void conv_w(const float* W, int K, int N, bf16_t* Wt, int NP, LAS float* scr, int gw, int ngw, int lane) {
;     ...
;     for (int it = gw; it < nitems; it += ngw) {
;         const int kb = it / nblk, nb = it % nblk, k0 = 64 * kb, np0 = 32 * nb, n0 = wmap<MODE>(np0);
; #pragma unroll 8
;         for (int i = 0; i < 32; ++i) { const int kk = 2 * i + (lane >> 5); scr[kk * 33 + (lane & 31)] = n0 >= 0 ? W[(size_t)(k0 + kk) * N + n0 + (lane & 31)] : 0.f; }
;         asm volatile("s_waitcnt lgkmcnt(0)" ::: "memory");
.LBB0_32:
	s_or_b64 exec, exec, s[6:7]
	s_add_i32 s15, s15, 16
	s_waitcnt vmcnt(0)
	s_nop 0
	s_cmp_eq_u32 s15, 64
	v_add_u32_e32 v11, 0x840, v11
	s_cbranch_scc1 .LBB0_26
.LBB0_33:
	v_mov_b32_e32 v120, 0
	v_mov_b32_e32 v121, 0
	v_mov_b32_e32 v122, 0
	v_mov_b32_e32 v123, 0
	v_mov_b32_e32 v124, 0
	v_mov_b32_e32 v125, 0
	v_mov_b32_e32 v126, 0
	v_mov_b32_e32 v127, 0
	s_and_saveexec_b64 s[6:7], vcc
	s_cbranch_execz .Lmy_cw1_skip
	v_add_u32_e32 v22, s15, v4
	v_mad_i64_i32 v[22:23], s[16:17], v22, s13, v[12:13]
	global_load_dword v120, v[22:23], off
	v_add3_u32 v21, v4, s15, 2
	v_mad_i64_i32 v[22:23], s[16:17], v21, s13, v[12:13]
	global_load_dword v121, v[22:23], off
	v_add3_u32 v22, v4, s15, 4
	v_mad_i64_i32 v[22:23], s[16:17], v22, s13, v[12:13]
	global_load_dword v122, v[22:23], off
	v_add3_u32 v21, v4, s15, 6
	v_mad_i64_i32 v[22:23], s[16:17], v21, s13, v[12:13]
	global_load_dword v123, v[22:23], off
	v_add3_u32 v22, v4, s15, 8
	v_mad_i64_i32 v[22:23], s[16:17], v22, s13, v[12:13]
	global_load_dword v124, v[22:23], off
	v_add3_u32 v21, v4, s15, 10
	v_mad_i64_i32 v[22:23], s[16:17], v21, s13, v[12:13]
	global_load_dword v125, v[22:23], off
	v_add3_u32 v22, v4, s15, 12
	v_mad_i64_i32 v[22:23], s[16:17], v22, s13, v[12:13]
	global_load_dword v126, v[22:23], off
	v_add3_u32 v21, v4, s15, 14
	v_mad_i64_i32 v[22:23], s[16:17], v21, s13, v[12:13]
	global_load_dword v127, v[22:23], off

; template <int MODE> __device__ __forceinline__ void conv_w(const float* W, int K, int N, bf16_t* Wt, int NP, LAS float* scr, int gw, int ngw, int lane) {
;     ...
;     for (int it = gw; it < nitems; it += ngw) {
;         const int kb = it / nblk, nb = it % nblk, k0 = 64 * kb, np0 = 32 * nb, n0 = wmap<MODE>(np0);
; #pragma unroll 8
;         for (int i = 0; i < 32; ++i) { const int kk = 2 * i + (lane >> 5); scr[kk * 33 + (lane & 31)] = n0 >= 0 ? W[(size_t)(k0 + kk) * N + n0 + (lane & 31)] : 0.f; }
;         asm volatile("s_waitcnt lgkmcnt(0)" ::: "memory");
.LBB0_53:
	s_or_b64 exec, exec, s[6:7]
	s_add_i32 s10, s10, 16
	s_waitcnt vmcnt(0)
	s_nop 0
	s_cmp_eq_u32 s10, 64
	v_add_u32_e32 v20, 0x840, v20
	s_cbranch_scc1 .LBB0_51
.LBB0_54:
	v_mov_b32_e32 v120, 0
	v_mov_b32_e32 v121, 0
	v_mov_b32_e32 v122, 0
	v_mov_b32_e32 v123, 0
	v_mov_b32_e32 v124, 0
	v_mov_b32_e32 v125, 0
	v_mov_b32_e32 v126, 0
	v_mov_b32_e32 v127, 0
	s_and_saveexec_b64 s[6:7], vcc
	s_cbranch_execz .Lmy_cw2_skip
	v_add_u32_e32 v22, s10, v11
	v_ashrrev_i32_e32 v23, 31, v22
	v_lshlrev_b64 v[22:23], 12, v[22:23]
	v_lshl_add_u64 v[22:23], v[12:13], 0, v[22:23]
	global_load_dword v120, v[22:23], off
	v_add3_u32 v22, v11, s10, 2
	v_ashrrev_i32_e32 v23, 31, v22
	v_lshlrev_b64 v[22:23], 12, v[22:23]
	v_lshl_add_u64 v[22:23], v[12:13], 0, v[22:23]
	global_load_dword v121, v[22:23], off
	v_add3_u32 v22, v11, s10, 4
	v_ashrrev_i32_e32 v23, 31, v22
	v_lshlrev_b64 v[22:23], 12, v[22:23]
	v_lshl_add_u64 v[22:23], v[12:13], 0, v[22:23]
	global_load_dword v122, v[22:23], off
	v_add3_u32 v22, v11, s10, 6
	v_ashrrev_i32_e32 v23, 31, v22
	v_lshlrev_b64 v[22:23], 12, v[22:23]
	v_lshl_add_u64 v[22:23], v[12:13], 0, v[22:23]
	global_load_dword v123, v[22:23], off
	v_add3_u32 v22, v11, s10, 8
	v_ashrrev_i32_e32 v23, 31, v22
	v_lshlrev_b64 v[22:23], 12, v[22:23]
	v_lshl_add_u64 v[22:23], v[12:13], 0, v[22:23]
	global_load_dword v124, v[22:23], off
	v_add3_u32 v22, v11, s10, 10
	v_ashrrev_i32_e32 v23, 31, v22
	v_lshlrev_b64 v[22:23], 12, v[22:23]
	v_lshl_add_u64 v[22:23], v[12:13], 0, v[22:23]
	global_load_dword v125, v[22:23], off
	v_add3_u32 v22, v11, s10, 12
	v_ashrrev_i32_e32 v23, 31, v22
	v_lshlrev_b64 v[22:23], 12, v[22:23]
	v_lshl_add_u64 v[22:23], v[12:13], 0, v[22:23]
	global_load_dword v126, v[22:23], off
	v_add3_u32 v22, v11, s10, 14
	v_ashrrev_i32_e32 v23, 31, v22
	v_lshlrev_b64 v[22:23], 12, v[22:23]
	v_lshl_add_u64 v[22:23], v[12:13], 0, v[22:23]
	global_load_dword v127, v[22:23], off
.Lmy_cw2_skip:
	s_or_b64 exec, exec, s[6:7]
	s_waitcnt vmcnt(0)
	ds_write_b32 v20, v120
	ds_write_b32 v20, v121 offset:264
	ds_write_b32 v20, v122 offset:528
	ds_write_b32 v20, v123 offset:792
	ds_write_b32 v20, v124 offset:1056
	ds_write_b32 v20, v125 offset:1320
	ds_write_b32 v20, v126 offset:1584
	ds_write_b32 v20, v127 offset:1848
	s_branch .LBB0_53

; template <int MODE> __device__ __forceinline__ void conv_w(const float* W, int K, int N, bf16_t* Wt, int NP, LAS float* scr, int gw, int ngw, int lane) {
;     ...
;     for (int it = gw; it < nitems; it += ngw) {
;         const int kb = it / nblk, nb = it % nblk, k0 = 64 * kb, np0 = 32 * nb, n0 = wmap<MODE>(np0);
; #pragma unroll 8
;         for (int i = 0; i < 32; ++i) { const int kk = 2 * i + (lane >> 5); scr[kk * 33 + (lane & 31)] = n0 >= 0 ? W[(size_t)(k0 + kk) * N + n0 + (lane & 31)] : 0.f; }
;         asm volatile("s_waitcnt lgkmcnt(0)" ::: "memory");
.LBB0_74:
	s_or_b64 exec, exec, s[6:7]
	s_add_i32 s11, s11, 16
	s_waitcnt vmcnt(0)
	s_nop 0
	s_cmp_eq_u32 s11, 64
	v_add_u32_e32 v20, 0x840, v20
	s_cbranch_scc1 .LBB0_72
.LBB0_75:
	v_mov_b32_e32 v120, 0
	v_mov_b32_e32 v121, 0
	v_mov_b32_e32 v122, 0
	v_mov_b32_e32 v123, 0
	v_mov_b32_e32 v124, 0
	v_mov_b32_e32 v125, 0
	v_mov_b32_e32 v126, 0
	v_mov_b32_e32 v127, 0
	s_and_saveexec_b64 s[6:7], vcc
	s_cbranch_execz .Lmy_cw3_skip
	v_add_u32_e32 v22, s11, v11
	v_ashrrev_i32_e32 v23, 31, v22
	v_lshlrev_b64 v[22:23], 12, v[22:23]
	v_lshl_add_u64 v[22:23], v[12:13], 0, v[22:23]
	global_load_dword v120, v[22:23], off
	v_add3_u32 v22, v11, s11, 2
	v_ashrrev_i32_e32 v23, 31, v22
	v_lshlrev_b64 v[22:23], 12, v[22:23]
	v_lshl_add_u64 v[22:23], v[12:13], 0, v[22:23]
	global_load_dword v121, v[22:23], off
	v_add3_u32 v22, v11, s11, 4
	v_ashrrev_i32_e32 v23, 31, v22
	v_lshlrev_b64 v[22:23], 12, v[22:23]
	v_lshl_add_u64 v[22:23], v[12:13], 0, v[22:23]
	global_load_dword v122, v[22:23], off
	v_add3_u32 v22, v11, s11, 6
	v_ashrrev_i32_e32 v23, 31, v22
	v_lshlrev_b64 v[22:23], 12, v[22:23]
	v_lshl_add_u64 v[22:23], v[12:13], 0, v[22:23]
	global_load_dword v123, v[22:23], off
	v_add3_u32 v22, v11, s11, 8
	v_ashrrev_i32_e32 v23, 31, v22
	v_lshlrev_b64 v[22:23], 12, v[22:23]
	v_lshl_add_u64 v[22:23], v[12:13], 0, v[22:23]
	global_load_dword v124, v[22:23], off
	v_add3_u32 v22, v11, s11, 10
	v_ashrrev_i32_e32 v23, 31, v22
	v_lshlrev_b64 v[22:23], 12, v[22:23]
	v_lshl_add_u64 v[22:23], v[12:13], 0, v[22:23]
	global_load_dword v125, v[22:23], off
	v_add3_u32 v22, v11, s11, 12
	v_ashrrev_i32_e32 v23, 31, v22
	v_lshlrev_b64 v[22:23], 12, v[22:23]
	v_lshl_add_u64 v[22:23], v[12:13], 0, v[22:23]
	global_load_dword v126, v[22:23], off
	v_add3_u32 v22, v11, s11, 14
	v_ashrrev_i32_e32 v23, 31, v22
	v_lshlrev_b64 v[22:23], 12, v[22:23]
	v_lshl_add_u64 v[22:23], v[12:13], 0, v[22:23]
	global_load_dword v127, v[22:23], off

; template <int MODE> __device__ __forceinline__ void conv_w(const float* W, int K, int N, bf16_t* Wt, int NP, LAS float* scr, int gw, int ngw, int lane) {
;     ...
;     for (int it = gw; it < nitems; it += ngw) {
;         const int kb = it / nblk, nb = it % nblk, k0 = 64 * kb, np0 = 32 * nb, n0 = wmap<MODE>(np0);
; #pragma unroll 8
;         for (int i = 0; i < 32; ++i) { const int kk = 2 * i + (lane >> 5); scr[kk * 33 + (lane & 31)] = n0 >= 0 ? W[(size_t)(k0 + kk) * N + n0 + (lane & 31)] : 0.f; }
;         asm volatile("s_waitcnt lgkmcnt(0)" ::: "memory");
.LBB0_95:
	s_or_b64 exec, exec, s[10:11]
	s_add_u32 s6, s6, 0x58000
	s_addc_u32 s7, s7, 0
	s_waitcnt vmcnt(0)
	s_nop 0
	s_cmp_eq_u32 s6, 0x160000
	v_add_u32_e32 v4, 0x840, v4
	s_cbranch_scc1 .LBB0_93
.LBB0_96:
	v_mov_b32_e32 v120, 0
	v_mov_b32_e32 v121, 0
	v_mov_b32_e32 v122, 0
	v_mov_b32_e32 v123, 0
	v_mov_b32_e32 v124, 0
	v_mov_b32_e32 v125, 0
	v_mov_b32_e32 v126, 0
	v_mov_b32_e32 v127, 0
	s_and_saveexec_b64 s[10:11], vcc
	s_cbranch_execz .Lmy_cw4_skip
	v_lshl_add_u64 v[50:51], v[26:27], 0, s[6:7]
	global_load_dword v120, v[50:51], off
	v_lshl_add_u64 v[50:51], v[24:25], 0, s[6:7]
	global_load_dword v121, v[50:51], off
	v_lshl_add_u64 v[50:51], v[22:23], 0, s[6:7]
	global_load_dword v122, v[50:51], off
	v_lshl_add_u64 v[50:51], v[20:21], 0, s[6:7]
	global_load_dword v123, v[50:51], off
	v_lshl_add_u64 v[50:51], v[18:19], 0, s[6:7]
	global_load_dword v124, v[50:51], off
	v_lshl_add_u64 v[50:51], v[16:17], 0, s[6:7]
	global_load_dword v125, v[50:51], off
	v_lshl_add_u64 v[50:51], v[14:15], 0, s[6:7]
	global_load_dword v126, v[50:51], off
	v_lshl_add_u64 v[50:51], v[12:13], 0, s[6:7]
	global_load_dword v127, v[50:51], off
.Lmy_cw4_skip:
	s_or_b64 exec, exec, s[10:11]
	s_waitcnt vmcnt(0)
	ds_write_b32 v4, v120
	ds_write_b32 v4, v121 offset:264
	ds_write_b32 v4, v122 offset:528
	ds_write_b32 v4, v123 offset:792
	ds_write_b32 v4, v124 offset:1056
	ds_write_b32 v4, v125 offset:1320
	ds_write_b32 v4, v126 offset:1584
	ds_write_b32 v4, v127 offset:1848
	s_branch .LBB0_95

; template <int MODE> __device__ __forceinline__ void conv_w(const float* W, int K, int N, bf16_t* Wt, int NP, LAS float* scr, int gw, int ngw, int lane) {
;     ...
;     for (int it = gw; it < nitems; it += ngw) {
;         const int kb = it / nblk, nb = it % nblk, k0 = 64 * kb, np0 = 32 * nb, n0 = wmap<MODE>(np0);
; #pragma unroll 8
;         for (int i = 0; i < 32; ++i) { const int kk = 2 * i + (lane >> 5); scr[kk * 33 + (lane & 31)] = n0 >= 0 ? W[(size_t)(k0 + kk) * N + n0 + (lane & 31)] : 0.f; }
;         asm volatile("s_waitcnt lgkmcnt(0)" ::: "memory");
.LBB0_116:
	s_or_b64 exec, exec, s[6:7]
	s_add_i32 s13, s13, 16
	s_waitcnt vmcnt(0)
	s_nop 0
	s_cmp_eq_u32 s13, 64
	v_add_u32_e32 v20, 0x840, v20
	s_cbranch_scc1 .LBB0_114
.LBB0_117:
	v_mov_b32_e32 v120, 0
	v_mov_b32_e32 v121, 0
	v_mov_b32_e32 v122, 0
	v_mov_b32_e32 v123, 0
	v_mov_b32_e32 v124, 0
	v_mov_b32_e32 v125, 0
	v_mov_b32_e32 v126, 0
	v_mov_b32_e32 v127, 0
	s_and_saveexec_b64 s[6:7], vcc
	s_cbranch_execz .Lmy_cw5_skip
	v_add_u32_e32 v22, s13, v11
	v_ashrrev_i32_e32 v23, 31, v22
	v_lshlrev_b64 v[22:23], 12, v[22:23]
	v_lshl_add_u64 v[22:23], v[12:13], 0, v[22:23]
	global_load_dword v120, v[22:23], off
	v_add3_u32 v22, v11, s13, 2
	v_ashrrev_i32_e32 v23, 31, v22
	v_lshlrev_b64 v[22:23], 12, v[22:23]
	v_lshl_add_u64 v[22:23], v[12:13], 0, v[22:23]
	global_load_dword v121, v[22:23], off
	v_add3_u32 v22, v11, s13, 4
	v_ashrrev_i32_e32 v23, 31, v22
	v_lshlrev_b64 v[22:23], 12, v[22:23]
	v_lshl_add_u64 v[22:23], v[12:13], 0, v[22:23]
	global_load_dword v122, v[22:23], off
	v_add3_u32 v22, v11, s13, 6
	v_ashrrev_i32_e32 v23, 31, v22
	v_lshlrev_b64 v[22:23], 12, v[22:23]
	v_lshl_add_u64 v[22:23], v[12:13], 0, v[22:23]
	global_load_dword v123, v[22:23], off
	v_add3_u32 v22, v11, s13, 8
	v_ashrrev_i32_e32 v23, 31, v22
	v_lshlrev_b64 v[22:23], 12, v[22:23]
	v_lshl_add_u64 v[22:23], v[12:13], 0, v[22:23]
	global_load_dword v124, v[22:23], off
	v_add3_u32 v22, v11, s13, 10
	v_ashrrev_i32_e32 v23, 31, v22
	v_lshlrev_b64 v[22:23], 12, v[22:23]
	v_lshl_add_u64 v[22:23], v[12:13], 0, v[22:23]
	global_load_dword v125, v[22:23], off
	v_add3_u32 v22, v11, s13, 12
	v_ashrrev_i32_e32 v23, 31, v22
	v_lshlrev_b64 v[22:23], 12, v[22:23]
	v_lshl_add_u64 v[22:23], v[12:13], 0, v[22:23]
	global_load_dword v126, v[22:23], off
	v_add3_u32 v22, v11, s13, 14
	v_ashrrev_i32_e32 v23, 31, v22
	v_lshlrev_b64 v[22:23], 12, v[22:23]
	v_lshl_add_u64 v[22:23], v[12:13], 0, v[22:23]
	global_load_dword v127, v[22:23], off

;     __device__ __forceinline__ const float* in(int k) const { return (const float*)(const GAS float*)ld(k); }
; __device__ __forceinline__ unsigned pk2(float lo, float hi) { f32x2_t v = {lo, hi}; bf16x2_t b = __builtin_convertvector(v, bf16x2_t); return __builtin_bit_cast(unsigned, b); }
; template <bool OUT_BF16> __device__ __forceinline__ void rms4(const float* x0, const float* g, void* o0, int lane) {
;     const f32x4* g4 = (const f32x4*)g; f32x4 v[4][4];
; #pragma unroll
;     for (int i = 0; i < 4; ++i)
; #pragma unroll
;         for (int j = 0; j < 4; ++j) v[i][j] = __builtin_nontemporal_load(&((const f32x4*)(x0 + (size_t)i * 1024))[64 * j + lane]);
; #pragma unroll
;     for (int i = 0; i < 4; ++i) {
;         float s = 0.f;
; #pragma unroll
;         for (int j = 0; j < 4; ++j) s += (v[i][j][0] * v[i][j][0] + v[i][j][1] * v[i][j][1]) + (v[i][j][2] * v[i][j][2] + v[i][j][3] * v[i][j][3]);
;         const float rstd = rsqrtf(wave_sum(s) * (1.f / 1024.f) + EPS);
; #pragma unroll
;         for (int j = 0; j < 4; ++j) {
;             const f32x4 o = v[i][j] * rstd * g4[64 * j + lane];
;             if (OUT_BF16) { u32x2 w; w.x = pk2(o[0], o[1]); w.y = pk2(o[2], o[3]); *(u32x2*)((bf16_t*)o0 + (size_t)i * 1024 + 256 * j + 4 * lane) = w; }
;             else ((f32x4*)((float*)o0 + (size_t)i * 1024))[64 * j + lane] = o;
;         }
;     }
; }
; __device__ __forceinline__ void phase0(LAS unsigned char* lds, const PTab& P, const int wid_s) {
;     ...
;     { const float* xp = P.in(0); const float* xs = P.in(1); const float* ga = P.in(7);
;       for (int r = 4 * gw; r < MT; r += 4 * ngw) rms4<true>(r < MP ? xp + (size_t)r * 1024 : xs + (size_t)(r - MP) * 1024, ga, H + (size_t)r * 1024, lane); }
.LBB0_139:
	s_or_b64 exec, exec, s[10:11]
	s_add_i32 s4, 0, 0x20400
	v_mov_b32_e32 v4, s4
	s_add_i32 s4, 0, 0x20408
	v_mov_b32_e32 v6, s4
	s_add_i32 s4, 0, 0x20438
	v_mov_b32_e32 v8, s4
	ds_read_b64 v[4:5], v4
	ds_read_b64 v[6:7], v6
	ds_read_b64 v[8:9], v8
	s_movk_i32 s10, 0x4080
	v_cmp_gt_i32_e32 vcc, s10, v3
	s_waitcnt lgkmcnt(2)
	v_readfirstlane_b32 s5, v5
	v_readfirstlane_b32 s4, v4
	s_waitcnt lgkmcnt(1)
	v_readfirstlane_b32 s7, v7
	v_readfirstlane_b32 s6, v6
	s_waitcnt lgkmcnt(0)
	v_readfirstlane_b32 s13, v9
	v_readfirstlane_b32 s12, v8
	v_mbcnt_lo_u32_b32 v147, -1, 0
	s_and_saveexec_b64 s[10:11], vcc
	s_cbranch_execz .LBB0_144
	v_lshlrev_b32_e32 v70, 2, v3
	v_mbcnt_hi_u32_b32 v3, -1, v147
	v_and_b32_e32 v5, 64, v3
	v_add_u32_e32 v5, 64, v5
	v_xor_b32_e32 v7, 1, v3
	v_cmp_lt_i32_e32 vcc, v7, v5
	v_mov_b32_e32 v67, 0
	v_lshl_add_u64 v[10:11], s[8:9], 0, v[66:67]
	v_cndmask_b32_e32 v7, v3, v7, vcc
	v_lshlrev_b32_e32 v69, 2, v7
	v_xor_b32_e32 v7, 2, v3
	v_cmp_lt_i32_e32 vcc, v7, v5
	s_mov_b64 s[14:15], 0x18e5800
	v_lshlrev_b32_e32 v66, 4, v2
	v_cndmask_b32_e32 v7, v3, v7, vcc
	v_lshlrev_b32_e32 v90, 2, v7
	v_xor_b32_e32 v7, 4, v3
	v_cmp_lt_i32_e32 vcc, v7, v5
	v_ashrrev_i32_e32 v71, 31, v70
	v_lshl_add_u64 v[72:73], v[10:11], 0, s[14:15]
	v_cndmask_b32_e32 v7, v3, v7, vcc
	v_lshlrev_b32_e32 v91, 2, v7
	v_xor_b32_e32 v7, 8, v3
	v_cmp_lt_i32_e32 vcc, v7, v5
	v_lshl_add_u64 v[74:75], s[12:13], 0, v[66:67]
	s_lshl_b32 s12, s33, 5
	v_cndmask_b32_e32 v7, v3, v7, vcc
	v_lshlrev_b32_e32 v92, 2, v7
	v_xor_b32_e32 v7, 16, v3
	v_cmp_lt_i32_e32 vcc, v7, v5
	v_lshlrev_b64 v[10:11], 12, v[70:71]
	v_or_b32_e32 v4, 64, v2
	v_cndmask_b32_e32 v7, v3, v7, vcc
	v_lshlrev_b32_e32 v93, 2, v7
	v_xor_b32_e32 v7, 32, v3
	v_cmp_lt_i32_e32 vcc, v7, v5
	v_or_b32_e32 v6, 0x80, v2
	v_or_b32_e32 v8, 0xc0, v2
	v_cndmask_b32_e32 v3, v3, v7, vcc
	s_ashr_i32 s13, s12, 31
	v_lshl_add_u64 v[76:77], s[4:5], 0, v[10:11]
	s_mov_b32 s4, 0x358637bd
	v_lshlrev_b32_e32 v94, 2, v3
	s_lshl_b64 s[14:15], s[12:13], 12
	s_mov_b64 s[16:17], 0
	s_mov_b32 s19, 0xffff
	v_lshlrev_b32_e32 v78, 4, v2
	v_mov_b32_e32 v79, v67
	s_mov_b64 s[20:21], 0x1000
	v_lshlrev_b32_e32 v80, 4, v4
	v_mov_b32_e32 v81, v67
	v_lshlrev_b32_e32 v82, 4, v6
	v_mov_b32_e32 v83, v67
	v_lshlrev_b32_e32 v84, 4, v8
	v_mov_b32_e32 v85, v67
	s_mov_b64 s[22:23], 0x2000
	s_mov_b64 s[24:25], 0x3000
	s_mov_b32 s26, 0x3a800000
	v_mov_b64_e32 v[86:87], s[4:5]
	s_mov_b32 s27, 0x800000
	s_movk_i32 s30, 0x1000
	s_mov_b32 s31, 0x101ff
	global_load_dwordx4 v[130:133], v[74:75], off
	global_load_dwordx4 v[134:137], v[74:75], off offset:1024
	global_load_dwordx4 v[138:141], v[74:75], off offset:2048
	global_load_dwordx4 v[142:145], v[74:75], off offset:3072
	s_waitcnt vmcnt(0)
	s_branch .LBB0_142
.LBB0_141:
	s_or_b64 exec, exec, s[4:5]
	v_lshl_add_u64 v[2:3], v[6:7], 0, v[78:79]
	global_load_dwordx4 v[14:17], v[2:3], off nt
	global_load_dwordx4 v[10:13], v[2:3], off offset:1024 nt
	global_load_dwordx4 v[58:61], v[2:3], off offset:2048 nt
	global_load_dwordx4 v[50:53], v[2:3], off offset:3072 nt
	v_lshl_add_u64 v[2:3], v[6:7], 0, s[20:21]
	v_lshl_add_u64 v[4:5], v[2:3], 0, v[78:79]
	global_load_dwordx4 v[42:45], v[4:5], off nt
	v_lshl_add_u64 v[4:5], v[2:3], 0, v[80:81]
	global_load_dwordx4 v[34:37], v[4:5], off nt
	v_lshl_add_u64 v[18:19], v[2:3], 0, v[82:83]
	v_lshl_add_u64 v[20:21], v[2:3], 0, v[84:85]
	global_load_dwordx4 v[46:49], v[18:19], off nt
	global_load_dwordx4 v[2:5], v[20:21], off nt
	v_lshlrev_b64 v[8:9], 11, v[8:9]
	v_lshl_add_u64 v[70:71], v[70:71], 0, s[12:13]
	v_lshl_add_u64 v[76:77], v[76:77], 0, s[14:15]
	s_waitcnt vmcnt(7)
	v_pk_mul_f32 v[18:19], v[16:17], v[16:17]
	v_pk_mul_f32 v[20:21], v[14:15], v[14:15]
	s_waitcnt vmcnt(6)
	v_pk_mul_f32 v[22:23], v[12:13], v[12:13]
	v_pk_mul_f32 v[24:25], v[10:11], v[10:11]
	v_pk_mov_b32 v[30:31], v[20:21], v[18:19] op_sel:[1,0]
	v_mov_b32_e32 v21, v19
	v_pk_mov_b32 v[18:19], v[24:25], v[22:23] op_sel:[1,0]
	v_mov_b32_e32 v25, v23
	s_waitcnt vmcnt(3)
	v_pk_mul_f32 v[22:23], v[44:45], v[44:45]
	v_pk_mul_f32 v[32:33], v[42:43], v[42:43]
	s_waitcnt vmcnt(2)
	v_pk_mul_f32 v[38:39], v[36:37], v[36:37]
	v_pk_mul_f32 v[40:41], v[34:35], v[34:35]
	v_pk_add_f32 v[18:19], v[18:19], v[24:25]
	v_pk_mov_b32 v[24:25], v[32:33], v[22:23] op_sel:[1,0]
	v_mov_b32_e32 v33, v23
	v_pk_mov_b32 v[22:23], v[40:41], v[38:39] op_sel:[1,0]
	v_mov_b32_e32 v41, v39
	v_mul_f32_e32 v26, v59, v59
	v_mul_f32_e32 v55, v52, v52
	v_mul_f32_e32 v28, v61, v61
	v_mul_f32_e32 v57, v53, v53
	s_waitcnt vmcnt(1)
	v_mul_f32_e32 v54, v47, v47
	v_mul_f32_e32 v56, v49, v49
	v_pk_add_f32 v[20:21], v[30:31], v[20:21]
	v_pk_add_f32 v[24:25], v[24:25], v[32:33]
	v_pk_add_f32 v[22:23], v[22:23], v[40:41]
	v_mul_f32_e32 v62, v50, v50
	v_mul_f32_e32 v63, v51, v51
	v_pk_fma_f32 v[26:27], v[58:59], v[58:59], v[26:27] op_sel_hi:[1,1,0]
	v_pk_fma_f32 v[28:29], v[60:61], v[60:61], v[28:29] op_sel_hi:[1,1,0]
	s_waitcnt vmcnt(0)
	v_mul_f32_e32 v64, v4, v4
	v_mul_f32_e32 v65, v5, v5
	v_mul_f32_e32 v66, v2, v2
	v_mul_f32_e32 v88, v3, v3
	v_pk_fma_f32 v[30:31], v[46:47], v[46:47], v[54:55] op_sel_hi:[1,1,0]
	v_pk_fma_f32 v[38:39], v[48:49], v[48:49], v[56:57] op_sel_hi:[1,1,0]
	v_pk_add_f32 v[20:21], v[20:21], v[20:21] op_sel:[0,1] op_sel_hi:[1,0]
	v_pk_add_f32 v[18:19], v[18:19], v[18:19] op_sel:[0,1] op_sel_hi:[1,0]
	v_pk_add_f32 v[24:25], v[24:25], v[24:25] op_sel:[0,1] op_sel_hi:[1,0]
	v_pk_add_f32 v[22:23], v[22:23], v[22:23] op_sel:[0,1] op_sel_hi:[1,0]
	v_mov_b32_e32 v27, v55
	v_mov_b32_e32 v29, v57
	v_mov_b32_e32 v31, v64
	v_mov_b32_e32 v39, v65
	v_mov_b32_e32 v21, v62
	v_mov_b32_e32 v19, v63
	v_mov_b32_e32 v25, v66
	v_mov_b32_e32 v23, v88
	v_pk_add_f32 v[26:27], v[26:27], v[28:29]
	v_pk_add_f32 v[28:29], v[30:31], v[38:39]
	v_pk_add_f32 v[18:19], v[20:21], v[18:19]
	v_pk_add_f32 v[20:21], v[24:25], v[22:23]
	v_pk_add_f32 v[18:19], v[18:19], v[26:27]
	v_pk_add_f32 v[20:21], v[20:21], v[28:29]
	v_mov_b32_e32 v23, v18
	v_mov_b32_e32 v22, v20
	v_mov_b32_e32 v18, v21
	v_pk_add_f32 v[18:19], v[22:23], v[18:19]
	ds_bpermute_b32 v21, v69, v19
	ds_bpermute_b32 v20, v69, v18
	v_lshl_add_u64 v[22:23], v[6:7], 0, s[22:23]
	v_lshl_add_u64 v[6:7], v[6:7], 0, s[24:25]
	v_lshl_add_u64 v[100:101], v[6:7], 0, v[78:79]
	v_lshl_add_u64 v[102:103], v[6:7], 0, v[80:81]
	s_waitcnt lgkmcnt(0)
; __device__ __forceinline__ unsigned pk2(float lo, float hi) { f32x2_t v = {lo, hi}; bf16x2_t b = __builtin_convertvector(v, bf16x2_t); return __builtin_bit_cast(unsigned, b); }
; template <bool OUT_BF16> __device__ __forceinline__ void rms4(const float* x0, const float* g, void* o0, int lane) {
;     const f32x4* g4 = (const f32x4*)g; f32x4 v[4][4];
; #pragma unroll
;     for (int i = 0; i < 4; ++i)
; #pragma unroll
;         for (int j = 0; j < 4; ++j) v[i][j] = __builtin_nontemporal_load(&((const f32x4*)(x0 + (size_t)i * 1024))[64 * j + lane]);
; #pragma unroll
;     for (int i = 0; i < 4; ++i) {
;         float s = 0.f;
; #pragma unroll
;         for (int j = 0; j < 4; ++j) s += (v[i][j][0] * v[i][j][0] + v[i][j][1] * v[i][j][1]) + (v[i][j][2] * v[i][j][2] + v[i][j][3] * v[i][j][3]);
;         const float rstd = rsqrtf(wave_sum(s) * (1.f / 1024.f) + EPS);
; #pragma unroll
;         for (int j = 0; j < 4; ++j) {
;             const f32x4 o = v[i][j] * rstd * g4[64 * j + lane];
;             if (OUT_BF16) { u32x2 w; w.x = pk2(o[0], o[1]); w.y = pk2(o[2], o[3]); *(u32x2*)((bf16_t*)o0 + (size_t)i * 1024 + 256 * j + 4 * lane) = w; }
;             else ((f32x4*)((float*)o0 + (size_t)i * 1024))[64 * j + lane] = o;
;         }
;     }
; }
	v_pk_add_f32 v[18:19], v[18:19], v[20:21]
	ds_bpermute_b32 v21, v90, v19
	ds_bpermute_b32 v20, v90, v18
	v_lshl_add_u64 v[104:105], v[6:7], 0, v[82:83]
	v_lshl_add_u64 v[106:107], v[6:7], 0, v[84:85]
	v_lshl_add_u64 v[88:89], v[72:73], 0, v[8:9]
	v_lshl_add_u64 v[24:25], v[22:23], 0, v[78:79]
	s_waitcnt lgkmcnt(0)
	v_pk_add_f32 v[18:19], v[18:19], v[20:21]
	ds_bpermute_b32 v21, v91, v19
	ds_bpermute_b32 v20, v91, v18
	v_lshl_add_u64 v[26:27], v[22:23], 0, v[80:81]
	v_lshl_add_u64 v[28:29], v[22:23], 0, v[82:83]
	v_lshl_add_u64 v[22:23], v[22:23], 0, v[84:85]
	global_load_dwordx4 v[62:65], v[24:25], off nt
	global_load_dwordx4 v[54:57], v[26:27], off nt
	global_load_dwordx4 v[38:41], v[28:29], off nt
	global_load_dwordx4 v[30:33], v[22:23], off nt
	s_waitcnt lgkmcnt(0)
	v_pk_add_f32 v[18:19], v[18:19], v[20:21]
	ds_bpermute_b32 v21, v92, v19
	ds_bpermute_b32 v20, v92, v18
	s_waitcnt lgkmcnt(0)
	v_pk_add_f32 v[18:19], v[18:19], v[20:21]
	ds_bpermute_b32 v21, v93, v19
	ds_bpermute_b32 v20, v93, v18
	s_waitcnt lgkmcnt(0)
	v_pk_add_f32 v[6:7], v[18:19], v[20:21]
	ds_bpermute_b32 v9, v94, v7
	ds_bpermute_b32 v8, v94, v6
	s_waitcnt lgkmcnt(0)
	v_pk_add_f32 v[6:7], v[6:7], v[8:9]
	s_nop 0
	v_pk_fma_f32 v[108:109], v[6:7], s[26:27], v[86:87] op_sel_hi:[1,0,0]
	s_nop 0
	v_mul_f32_e32 v6, 0x4b800000, v109
	v_cmp_gt_f32_e32 vcc, s27, v109
	s_nop 1
	v_cndmask_b32_e32 v6, v109, v6, vcc
	v_rsq_f32_e32 v66, v6
	global_load_dwordx4 v[26:29], v[100:101], off nt
	global_load_dwordx4 v[22:25], v[102:103], off nt
	global_load_dwordx4 v[18:21], v[104:105], off nt
	global_load_dwordx4 v[6:9], v[106:107], off nt
	v_mul_f32_e32 v95, 0x45800000, v66
	v_cndmask_b32_e32 v66, v66, v95, vcc
	v_pk_mul_f32 v[14:15], v[14:15], v[66:67] op_sel_hi:[1,0]
	v_pk_mul_f32 v[16:17], v[16:17], v[66:67] op_sel_hi:[1,0]
	s_nop 0
	v_pk_mul_f32 v[14:15], v[130:131], v[14:15]
	v_pk_mul_f32 v[16:17], v[132:133], v[16:17]
	v_cvt_pk_bf16_f32 v14, v14, v15
	v_cvt_pk_bf16_f32 v15, v16, v17
	global_store_dwordx2 v[88:89], v[14:15], off
	v_pk_mul_f32 v[10:11], v[10:11], v[66:67] op_sel_hi:[1,0]
	v_pk_mul_f32 v[12:13], v[12:13], v[66:67] op_sel_hi:[1,0]
	v_cmp_gt_f32_e32 vcc, s27, v108
	s_waitcnt vmcnt(5)
	v_mul_f32_e32 v95, v33, v33
	v_mul_f32_e32 v100, v30, v30
	v_mul_f32_e32 v101, v31, v31
	s_waitcnt vmcnt(1)
	v_mul_f32_e32 v98, v8, v8
	v_mul_f32_e32 v99, v9, v9
	v_mul_f32_e32 v102, v6, v6
	v_mul_f32_e32 v103, v7, v7
	s_nop 0
	v_pk_mul_f32 v[12:13], v[136:137], v[12:13]
	v_pk_mul_f32 v[10:11], v[134:135], v[10:11]
	v_pk_mul_f32 v[14:15], v[58:59], v[66:67] op_sel_hi:[1,0]
	v_cvt_pk_bf16_f32 v10, v10, v11
	v_cvt_pk_bf16_f32 v11, v12, v13
	global_store_dwordx2 v[88:89], v[10:11], off offset:512
	v_pk_mul_f32 v[16:17], v[60:61], v[66:67] op_sel_hi:[1,0]
	v_mul_f32_e32 v58, v41, v41
	v_mul_f32_e32 v60, v19, v19
	s_nop 0
	v_pk_mul_f32 v[12:13], v[140:141], v[16:17]
	v_pk_mul_f32 v[10:11], v[138:139], v[14:15]
	v_pk_mul_f32 v[14:15], v[50:51], v[66:67] op_sel_hi:[1,0]
	v_cvt_pk_bf16_f32 v10, v10, v11
	v_cvt_pk_bf16_f32 v11, v12, v13
	global_store_dwordx2 v[88:89], v[10:11], off offset:1024
	v_pk_mul_f32 v[16:17], v[52:53], v[66:67] op_sel_hi:[1,0]
	v_pk_mul_f32 v[50:51], v[22:23], v[22:23]
	v_mul_f32_e32 v52, v39, v39
	v_mul_f32_e32 v66, v21, v21
	s_nop 0
	v_pk_mul_f32 v[12:13], v[144:145], v[16:17]
	v_pk_mul_f32 v[10:11], v[142:143], v[14:15]
	v_mul_f32_e32 v14, 0x4b800000, v108
	v_cvt_pk_bf16_f32 v10, v10, v11
	v_cvt_pk_bf16_f32 v11, v12, v13
	global_store_dwordx2 v[88:89], v[10:11], off offset:1536
	v_cndmask_b32_e32 v14, v108, v14, vcc
	v_rsq_f32_e32 v14, v14
	s_nop 0
	v_mul_f32_e32 v15, 0x45800000, v14
	v_cndmask_b32_e32 v14, v14, v15, vcc
	v_pk_mul_f32 v[16:17], v[42:43], v[14:15] op_sel_hi:[1,0]
	v_pk_mul_f32 v[42:43], v[44:45], v[14:15] op_sel_hi:[1,0]
	v_pk_mul_f32 v[44:45], v[28:29], v[28:29]
	s_nop 0
	v_pk_mul_f32 v[12:13], v[132:133], v[42:43]
	v_pk_mul_f32 v[10:11], v[130:131], v[16:17]
	v_pk_mul_f32 v[16:17], v[34:35], v[14:15] op_sel_hi:[1,0]
	v_cvt_pk_bf16_f32 v10, v10, v11
	v_cvt_pk_bf16_f32 v11, v12, v13
	global_store_dwordx2 v[88:89], v[10:11], off offset:2048
	v_pk_mul_f32 v[34:35], v[36:37], v[14:15] op_sel_hi:[1,0]
	v_pk_mul_f32 v[36:37], v[56:57], v[56:57]
	v_pk_mul_f32 v[42:43], v[54:55], v[54:55]
	s_nop 0
	v_pk_mul_f32 v[12:13], v[136:137], v[34:35]
	v_pk_mul_f32 v[10:11], v[134:135], v[16:17]
	v_pk_mul_f32 v[16:17], v[46:47], v[14:15] op_sel_hi:[1,0]
	v_cvt_pk_bf16_f32 v10, v10, v11
	v_cvt_pk_bf16_f32 v11, v12, v13
	global_store_dwordx2 v[88:89], v[10:11], off offset:2560
	v_pk_mul_f32 v[34:35], v[48:49], v[14:15] op_sel_hi:[1,0]
	v_mul_f32_e32 v15, v32, v32
	v_pk_mul_f32 v[2:3], v[2:3], v[14:15] op_sel_hi:[1,0]
	v_pk_mul_f32 v[4:5], v[4:5], v[14:15] op_sel_hi:[1,0]
	v_pk_mul_f32 v[46:47], v[26:27], v[26:27]
	v_pk_mul_f32 v[48:49], v[24:25], v[24:25]
	s_nop 0
	v_pk_mul_f32 v[12:13], v[140:141], v[34:35]
	v_pk_mul_f32 v[10:11], v[138:139], v[16:17]
	v_pk_mul_f32 v[16:17], v[64:65], v[64:65]
	v_cvt_pk_bf16_f32 v10, v10, v11
	v_cvt_pk_bf16_f32 v11, v12, v13
	global_store_dwordx2 v[88:89], v[10:11], off offset:3072
	v_pk_mul_f32 v[34:35], v[62:63], v[62:63]
	s_nop 0
	v_pk_mul_f32 v[4:5], v[144:145], v[4:5]
	v_pk_mul_f32 v[2:3], v[142:143], v[2:3]
	v_pk_mov_b32 v[96:97], v[34:35], v[16:17] op_sel:[1,0]
	v_cvt_pk_bf16_f32 v2, v2, v3
	v_cvt_pk_bf16_f32 v3, v4, v5
	global_store_dwordx2 v[88:89], v[2:3], off offset:3584
	v_mov_b32_e32 v35, v17
	v_pk_mov_b32 v[16:17], v[42:43], v[36:37] op_sel:[1,0]
	v_mov_b32_e32 v43, v37
	v_pk_mov_b32 v[36:37], v[46:47], v[44:45] op_sel:[1,0]
	v_mov_b32_e32 v47, v45
	v_pk_mov_b32 v[44:45], v[50:51], v[48:49] op_sel:[1,0]
	v_mov_b32_e32 v51, v49
	v_pk_add_f32 v[34:35], v[96:97], v[34:35]
	v_pk_add_f32 v[16:17], v[16:17], v[42:43]
	v_pk_add_f32 v[10:11], v[36:37], v[46:47]
	v_pk_add_f32 v[12:13], v[44:45], v[50:51]
	v_pk_fma_f32 v[48:49], v[38:39], v[38:39], v[52:53] op_sel_hi:[1,1,0]
	v_pk_fma_f32 v[52:53], v[40:41], v[40:41], v[58:59] op_sel_hi:[1,1,0]
	v_pk_fma_f32 v[58:59], v[18:19], v[18:19], v[60:61] op_sel_hi:[1,1,0]
	v_pk_fma_f32 v[60:61], v[20:21], v[20:21], v[66:67] op_sel_hi:[1,1,0]
	v_pk_add_f32 v[34:35], v[34:35], v[34:35] op_sel:[0,1] op_sel_hi:[1,0]
	v_pk_add_f32 v[16:17], v[16:17], v[16:17] op_sel:[0,1] op_sel_hi:[1,0]
	v_pk_add_f32 v[10:11], v[10:11], v[10:11] op_sel:[0,1] op_sel_hi:[1,0]
	v_pk_add_f32 v[12:13], v[12:13], v[12:13] op_sel:[0,1] op_sel_hi:[1,0]
	v_mov_b32_e32 v49, v15
	v_mov_b32_e32 v53, v95
	v_mov_b32_e32 v59, v98
	v_mov_b32_e32 v61, v99
	v_mov_b32_e32 v35, v100
	v_mov_b32_e32 v17, v101
	v_mov_b32_e32 v11, v102
	v_mov_b32_e32 v13, v103
	v_pk_add_f32 v[14:15], v[48:49], v[52:53]
	v_pk_add_f32 v[36:37], v[58:59], v[60:61]
	v_pk_add_f32 v[16:17], v[34:35], v[16:17]
	v_pk_add_f32 v[10:11], v[10:11], v[12:13]
	v_pk_add_f32 v[12:13], v[16:17], v[14:15]
	v_pk_add_f32 v[10:11], v[10:11], v[36:37]
	v_mov_b32_e32 v15, v12
	v_mov_b32_e32 v14, v10
	v_mov_b32_e32 v12, v11
	v_pk_add_f32 v[10:11], v[14:15], v[12:13]
	ds_bpermute_b32 v13, v69, v11
	ds_bpermute_b32 v12, v69, v10
	s_waitcnt lgkmcnt(0)
; __device__ __forceinline__ unsigned pk2(float lo, float hi) { f32x2_t v = {lo, hi}; bf16x2_t b = __builtin_convertvector(v, bf16x2_t); return __builtin_bit_cast(unsigned, b); }
; template <bool OUT_BF16> __device__ __forceinline__ void rms4(const float* x0, const float* g, void* o0, int lane) {
;     const f32x4* g4 = (const f32x4*)g; f32x4 v[4][4];
; #pragma unroll
;     for (int i = 0; i < 4; ++i)
; #pragma unroll
;         for (int j = 0; j < 4; ++j) v[i][j] = __builtin_nontemporal_load(&((const f32x4*)(x0 + (size_t)i * 1024))[64 * j + lane]);
; #pragma unroll
;     for (int i = 0; i < 4; ++i) {
;         float s = 0.f;
; #pragma unroll
;         for (int j = 0; j < 4; ++j) s += (v[i][j][0] * v[i][j][0] + v[i][j][1] * v[i][j][1]) + (v[i][j][2] * v[i][j][2] + v[i][j][3] * v[i][j][3]);
;         const float rstd = rsqrtf(wave_sum(s) * (1.f / 1024.f) + EPS);
; #pragma unroll
;         for (int j = 0; j < 4; ++j) {
;             const f32x4 o = v[i][j] * rstd * g4[64 * j + lane];
;             if (OUT_BF16) { u32x2 w; w.x = pk2(o[0], o[1]); w.y = pk2(o[2], o[3]); *(u32x2*)((bf16_t*)o0 + (size_t)i * 1024 + 256 * j + 4 * lane) = w; }
;             else ((f32x4*)((float*)o0 + (size_t)i * 1024))[64 * j + lane] = o;
;         }
;     }
; }
	v_pk_add_f32 v[10:11], v[10:11], v[12:13]
	ds_bpermute_b32 v13, v90, v11
	ds_bpermute_b32 v12, v90, v10
	s_waitcnt lgkmcnt(0)
	v_pk_add_f32 v[10:11], v[10:11], v[12:13]
	ds_bpermute_b32 v13, v91, v11
	ds_bpermute_b32 v12, v91, v10
	s_waitcnt lgkmcnt(0)
	v_pk_add_f32 v[10:11], v[10:11], v[12:13]
	ds_bpermute_b32 v13, v92, v11
	ds_bpermute_b32 v12, v92, v10
	s_waitcnt lgkmcnt(0)
	v_pk_add_f32 v[10:11], v[10:11], v[12:13]
	ds_bpermute_b32 v13, v93, v11
	ds_bpermute_b32 v12, v93, v10
	s_waitcnt lgkmcnt(0)
	v_pk_add_f32 v[10:11], v[10:11], v[12:13]
	ds_bpermute_b32 v13, v94, v11
	ds_bpermute_b32 v12, v94, v10
	s_waitcnt lgkmcnt(0)
	v_pk_add_f32 v[10:11], v[10:11], v[12:13]
	s_nop 0
	v_pk_fma_f32 v[10:11], v[10:11], s[26:27], v[86:87] op_sel_hi:[1,0,0]
	s_nop 0
	v_mul_f32_e32 v12, 0x4b800000, v11
	v_cmp_gt_f32_e32 vcc, s27, v11
	s_nop 1
	v_cndmask_b32_e32 v11, v11, v12, vcc
	v_rsq_f32_e32 v11, v11
	v_add_co_u32_e64 v12, s[4:5], s30, v88
	v_mul_f32_e32 v14, 0x45800000, v11
	v_cndmask_b32_e32 v14, v11, v14, vcc
	v_pk_mul_f32 v[16:17], v[62:63], v[14:15] op_sel_hi:[1,0]
	v_pk_mul_f32 v[34:35], v[64:65], v[14:15] op_sel_hi:[1,0]
	s_nop 0
	v_pk_mul_f32 v[2:3], v[130:131], v[16:17]
	v_pk_mul_f32 v[4:5], v[132:133], v[34:35]
	v_addc_co_u32_e64 v13, s[4:5], 0, v89, s[4:5]
	v_cvt_pk_bf16_f32 v2, v2, v3
	v_cvt_pk_bf16_f32 v3, v4, v5
	global_store_dwordx2 v[12:13], v[2:3], off
	v_pk_mul_f32 v[16:17], v[54:55], v[14:15] op_sel_hi:[1,0]
	v_pk_mul_f32 v[34:35], v[56:57], v[14:15] op_sel_hi:[1,0]
	v_mul_f32_e32 v11, 0x4b800000, v10
	v_cmp_gt_f32_e32 vcc, s27, v10
	s_nop 0
	v_pk_mul_f32 v[4:5], v[136:137], v[34:35]
	v_pk_mul_f32 v[2:3], v[134:135], v[16:17]
	v_pk_mul_f32 v[16:17], v[38:39], v[14:15] op_sel_hi:[1,0]
	v_cvt_pk_bf16_f32 v2, v2, v3
	v_cvt_pk_bf16_f32 v3, v4, v5
	global_store_dwordx2 v[12:13], v[2:3], off offset:512
	v_pk_mul_f32 v[34:35], v[40:41], v[14:15] op_sel_hi:[1,0]
	v_cndmask_b32_e32 v10, v10, v11, vcc
	v_rsq_f32_e32 v10, v10
	s_nop 0
	v_pk_mul_f32 v[4:5], v[140:141], v[34:35]
	v_pk_mul_f32 v[2:3], v[138:139], v[16:17]
	v_pk_mul_f32 v[16:17], v[30:31], v[14:15] op_sel_hi:[1,0]
	v_cvt_pk_bf16_f32 v2, v2, v3
	v_cvt_pk_bf16_f32 v3, v4, v5
	global_store_dwordx2 v[12:13], v[2:3], off offset:1024
	v_pk_mul_f32 v[14:15], v[32:33], v[14:15] op_sel_hi:[1,0]
	v_mul_f32_e32 v11, 0x45800000, v10
	v_cndmask_b32_e32 v10, v10, v11, vcc
	v_pk_mul_f32 v[6:7], v[6:7], v[10:11] op_sel_hi:[1,0]
	v_pk_mul_f32 v[8:9], v[8:9], v[10:11] op_sel_hi:[1,0]
	v_cmp_lt_i32_e32 vcc, s31, v70
	s_or_b64 s[16:17], vcc, s[16:17]
	s_nop 0
	v_pk_mul_f32 v[4:5], v[144:145], v[14:15]
	v_pk_mul_f32 v[2:3], v[142:143], v[16:17]
	v_pk_mul_f32 v[14:15], v[26:27], v[10:11] op_sel_hi:[1,0]
	v_cvt_pk_bf16_f32 v2, v2, v3
	v_cvt_pk_bf16_f32 v3, v4, v5
	global_store_dwordx2 v[12:13], v[2:3], off offset:1536
	v_pk_mul_f32 v[16:17], v[28:29], v[10:11] op_sel_hi:[1,0]
	s_nop 0
	v_pk_mul_f32 v[2:3], v[130:131], v[14:15]
	v_pk_mul_f32 v[4:5], v[132:133], v[16:17]
	v_cvt_pk_bf16_f32 v2, v2, v3
	v_cvt_pk_bf16_f32 v3, v4, v5
	global_store_dwordx2 v[12:13], v[2:3], off offset:2048
	v_pk_mul_f32 v[14:15], v[22:23], v[10:11] op_sel_hi:[1,0]
	v_pk_mul_f32 v[16:17], v[24:25], v[10:11] op_sel_hi:[1,0]
	s_nop 0
	v_pk_mul_f32 v[2:3], v[134:135], v[14:15]
	v_pk_mul_f32 v[4:5], v[136:137], v[16:17]
	v_cvt_pk_bf16_f32 v2, v2, v3
	v_cvt_pk_bf16_f32 v3, v4, v5
	global_store_dwordx2 v[12:13], v[2:3], off offset:2560
	v_pk_mul_f32 v[14:15], v[18:19], v[10:11] op_sel_hi:[1,0]
	v_pk_mul_f32 v[16:17], v[20:21], v[10:11] op_sel_hi:[1,0]
	s_nop 0
	v_pk_mul_f32 v[2:3], v[138:139], v[14:15]
	v_pk_mul_f32 v[4:5], v[140:141], v[16:17]
	v_cvt_pk_bf16_f32 v2, v2, v3
	v_cvt_pk_bf16_f32 v3, v4, v5
	global_store_dwordx2 v[12:13], v[2:3], off offset:3072
	s_nop 0
	v_pk_mul_f32 v[4:5], v[144:145], v[8:9]
	v_pk_mul_f32 v[2:3], v[142:143], v[6:7]
	s_nop 0
	v_cvt_pk_bf16_f32 v2, v2, v3
	v_cvt_pk_bf16_f32 v3, v4, v5
	global_store_dwordx2 v[12:13], v[2:3], off offset:3584
	s_andn2_b64 exec, exec, s[16:17]
	s_cbranch_execz .LBB0_144
